# residual-GEMM main loop also with two 32-MFMA phases per K-tile (on top of the up loop)
# baseline (speedup 1.0000x reference)
.LBB0_182:
	s_add_i32 s91, s2, 2
	s_add_u32 s12, s34, 0x80
	s_addc_u32 s3, s35, 0
	s_add_i32 s13, 0, 0x10000
	v_add_u32_e32 v142, s13, v183
	ds_read_b128 v[130:133], v142
	ds_read_b128 v[134:137], v142 offset:1024
	ds_read_b128 v[138:141], v142 offset:2048
	ds_read_b128 v[142:145], v142 offset:3072
	s_cmp_eq_u32 s88, s2
	s_cselect_b32 s2, s0, s12
	s_cselect_b32 s3, s1, s3
	s_cselect_b32 s43, s41, s90
	s_cselect_b32 s42, s40, s89
	v_lshl_add_u64 v[190:191], s[34:35], 0, v[174:175]
	s_add_i32 m0, s55, 0xc000
	ds_read_b128 v[146:149], v184
	ds_read_b128 v[150:153], v184 offset:1024
	ds_read_b128 v[154:157], v184 offset:2048
	ds_read_b128 v[158:161], v184 offset:3072
	ds_read_b128 v[162:165], v184 offset:4096
	ds_read_b128 v[166:169], v184 offset:5120
	ds_read_b128 v[178:181], v184 offset:6144
	ds_read_b128 v[186:189], v184 offset:7168
	global_load_lds_dwordx4 v[190:191], off
	v_lshl_add_u64 v[190:191], s[34:35], 0, v[176:177]
	s_add_i32 m0, s55, 0xe000
	s_nop 0
	global_load_lds_dwordx4 v[190:191], off
	s_waitcnt lgkmcnt(8)
	s_add_i32 s92, 0, 0x14000
	s_add_i32 s12, s13, s54
	v_add_u32_e32 v185, s92, v183
	ds_read_b128 v[190:193], v185
	ds_read_b128 v[194:197], v185 offset:1024
	ds_read_b128 v[198:201], v185 offset:2048
	ds_read_b128 v[226:229], v185 offset:3072
	s_barrier
	s_waitcnt lgkmcnt(0)
	s_waitcnt lgkmcnt(0)
	v_mfma_f32_16x16x32_bf16 v[126:129], v[130:133], v[146:149], v[126:129]
	v_mfma_f32_16x16x32_bf16 v[122:125], v[138:141], v[146:149], v[122:125]
	v_mfma_f32_16x16x32_bf16 v[118:121], v[130:133], v[154:157], v[118:121]
	v_mfma_f32_16x16x32_bf16 v[114:117], v[138:141], v[154:157], v[114:117]
	v_mfma_f32_16x16x32_bf16 v[110:113], v[130:133], v[162:165], v[110:113]
	v_mfma_f32_16x16x32_bf16 v[106:109], v[138:141], v[162:165], v[106:109]
	v_mfma_f32_16x16x32_bf16 v[102:105], v[130:133], v[178:181], v[102:105]
	v_mfma_f32_16x16x32_bf16 v[98:101], v[138:141], v[178:181], v[98:101]
	v_mfma_f32_16x16x32_bf16 v[126:129], v[134:137], v[150:153], v[126:129]
	v_mfma_f32_16x16x32_bf16 v[122:125], v[142:145], v[150:153], v[122:125]
	v_mfma_f32_16x16x32_bf16 v[118:121], v[134:137], v[158:161], v[118:121]
	v_mfma_f32_16x16x32_bf16 v[114:117], v[142:145], v[158:161], v[114:117]
	v_mfma_f32_16x16x32_bf16 v[110:113], v[134:137], v[166:169], v[110:113]
	v_mfma_f32_16x16x32_bf16 v[106:109], v[142:145], v[166:169], v[106:109]
	v_mfma_f32_16x16x32_bf16 v[102:105], v[134:137], v[186:189], v[102:105]
	v_mfma_f32_16x16x32_bf16 v[98:101], v[142:145], v[186:189], v[98:101]
	s_waitcnt lgkmcnt(0)
	s_waitcnt lgkmcnt(0)
	v_mfma_f32_16x16x32_bf16 v[62:65], v[190:193], v[146:149], v[62:65]
	v_mfma_f32_16x16x32_bf16 v[58:61], v[198:201], v[146:149], v[58:61]
	v_mfma_f32_16x16x32_bf16 v[54:57], v[190:193], v[154:157], v[54:57]
	v_mfma_f32_16x16x32_bf16 v[50:53], v[198:201], v[154:157], v[50:53]
	v_mfma_f32_16x16x32_bf16 v[46:49], v[190:193], v[162:165], v[46:49]
	v_mfma_f32_16x16x32_bf16 v[42:45], v[198:201], v[162:165], v[42:45]
	v_mfma_f32_16x16x32_bf16 v[38:41], v[190:193], v[178:181], v[38:41]
	v_mfma_f32_16x16x32_bf16 v[34:37], v[198:201], v[178:181], v[34:37]
	v_mfma_f32_16x16x32_bf16 v[62:65], v[194:197], v[150:153], v[62:65]
	v_mfma_f32_16x16x32_bf16 v[58:61], v[226:229], v[150:153], v[58:61]
	v_mfma_f32_16x16x32_bf16 v[54:57], v[194:197], v[158:161], v[54:57]
	v_mfma_f32_16x16x32_bf16 v[50:53], v[226:229], v[158:161], v[50:53]
	v_mfma_f32_16x16x32_bf16 v[46:49], v[194:197], v[166:169], v[46:49]
	v_mfma_f32_16x16x32_bf16 v[42:45], v[226:229], v[166:169], v[42:45]
	v_mfma_f32_16x16x32_bf16 v[38:41], v[194:197], v[186:189], v[38:41]
	v_mfma_f32_16x16x32_bf16 v[34:37], v[226:229], v[186:189], v[34:37]
	s_mov_b32 m0, s55
	v_lshl_add_u64 v[234:235], s[2:3], 0, v[170:171]
	s_barrier
	ds_read_b128 v[146:149], v184 offset:16384
	ds_read_b128 v[150:153], v184 offset:17408
	ds_read_b128 v[154:157], v184 offset:18432
	ds_read_b128 v[158:161], v184 offset:19456
	ds_read_b128 v[162:165], v184 offset:20480
	ds_read_b128 v[166:169], v184 offset:21504
	ds_read_b128 v[178:181], v184 offset:22528
	ds_read_b128 v[186:189], v184 offset:23552
	global_load_lds_dwordx4 v[234:235], off
	v_lshl_add_u64 v[236:237], s[2:3], 0, v[172:173]
	s_mov_b32 m0, s58
	s_nop 0
	global_load_lds_dwordx4 v[236:237], off
	v_lshl_add_u64 v[230:231], s[42:43], 0, v[170:171]
	s_mov_b32 m0, s12
	s_nop 0
	global_load_lds_dwordx4 v[230:231], off
	v_lshl_add_u64 v[232:233], s[42:43], 0, v[172:173]
	s_add_i32 m0, s12, 0x2000
	s_nop 0
	global_load_lds_dwordx4 v[232:233], off
	s_add_u32 s12, s42, s18
	s_addc_u32 s13, s43, 0
	s_add_i32 s42, s92, s54
	v_lshl_add_u64 v[242:243], s[12:13], 0, v[170:171]
	s_mov_b32 m0, s42
	v_lshl_add_u64 v[244:245], s[12:13], 0, v[172:173]
	global_load_lds_dwordx4 v[242:243], off
	s_add_i32 m0, s42, 0x2000
	s_nop 0
	global_load_lds_dwordx4 v[244:245], off
	s_waitcnt vmcnt(6)
	s_barrier
	s_waitcnt lgkmcnt(0)
	s_waitcnt lgkmcnt(0)
	v_mfma_f32_16x16x32_bf16 v[94:97], v[130:133], v[146:149], v[94:97]
	v_mfma_f32_16x16x32_bf16 v[90:93], v[138:141], v[146:149], v[90:93]
	v_mfma_f32_16x16x32_bf16 v[86:89], v[130:133], v[154:157], v[86:89]
	v_mfma_f32_16x16x32_bf16 v[82:85], v[138:141], v[154:157], v[82:85]
	v_mfma_f32_16x16x32_bf16 v[78:81], v[130:133], v[162:165], v[78:81]
	v_mfma_f32_16x16x32_bf16 v[74:77], v[138:141], v[162:165], v[74:77]
	v_mfma_f32_16x16x32_bf16 v[70:73], v[130:133], v[178:181], v[70:73]
	v_mfma_f32_16x16x32_bf16 v[66:69], v[138:141], v[178:181], v[66:69]
	v_mfma_f32_16x16x32_bf16 v[94:97], v[134:137], v[150:153], v[94:97]
	v_mfma_f32_16x16x32_bf16 v[90:93], v[142:145], v[150:153], v[90:93]
	v_mfma_f32_16x16x32_bf16 v[86:89], v[134:137], v[158:161], v[86:89]
	v_mfma_f32_16x16x32_bf16 v[82:85], v[142:145], v[158:161], v[82:85]
	v_mfma_f32_16x16x32_bf16 v[78:81], v[134:137], v[166:169], v[78:81]
	v_mfma_f32_16x16x32_bf16 v[74:77], v[142:145], v[166:169], v[74:77]
	v_mfma_f32_16x16x32_bf16 v[70:73], v[134:137], v[186:189], v[70:73]
	v_mfma_f32_16x16x32_bf16 v[66:69], v[142:145], v[186:189], v[66:69]
	v_mfma_f32_16x16x32_bf16 v[30:33], v[190:193], v[146:149], v[30:33]
	v_mfma_f32_16x16x32_bf16 v[26:29], v[198:201], v[146:149], v[26:29]
	v_mfma_f32_16x16x32_bf16 v[22:25], v[190:193], v[154:157], v[22:25]
	v_mfma_f32_16x16x32_bf16 v[18:21], v[198:201], v[154:157], v[18:21]
	v_mfma_f32_16x16x32_bf16 v[14:17], v[190:193], v[162:165], v[14:17]
	v_mfma_f32_16x16x32_bf16 v[10:13], v[198:201], v[162:165], v[10:13]
	v_mfma_f32_16x16x32_bf16 v[6:9], v[190:193], v[178:181], v[6:9]
	v_mfma_f32_16x16x32_bf16 v[2:5], v[198:201], v[178:181], v[2:5]
	v_mfma_f32_16x16x32_bf16 v[30:33], v[194:197], v[150:153], v[30:33]
	v_mfma_f32_16x16x32_bf16 v[26:29], v[226:229], v[150:153], v[26:29]
	v_mfma_f32_16x16x32_bf16 v[22:25], v[194:197], v[158:161], v[22:25]
	v_mfma_f32_16x16x32_bf16 v[18:21], v[226:229], v[158:161], v[18:21]
	v_mfma_f32_16x16x32_bf16 v[14:17], v[194:197], v[166:169], v[14:17]
	v_mfma_f32_16x16x32_bf16 v[10:13], v[226:229], v[166:169], v[10:13]
	v_mfma_f32_16x16x32_bf16 v[6:9], v[194:197], v[186:189], v[6:9]
	v_mfma_f32_16x16x32_bf16 v[2:5], v[226:229], v[186:189], v[2:5]
	s_add_i32 s12, 0, 0x18000
	v_add_u32_e32 v142, s12, v183
	s_barrier
	ds_read_b128 v[130:133], v142
	ds_read_b128 v[134:137], v142 offset:1024
	ds_read_b128 v[138:141], v142 offset:2048
	ds_read_b128 v[142:145], v142 offset:3072
	s_add_u32 s2, s2, s18
	s_addc_u32 s3, s3, 0
	s_mov_b32 m0, s59
	v_lshl_add_u64 v[190:191], s[2:3], 0, v[170:171]
	ds_read_b128 v[146:149], v184 offset:32768
	ds_read_b128 v[150:153], v184 offset:33792
	ds_read_b128 v[154:157], v184 offset:34816
	ds_read_b128 v[158:161], v184 offset:35840
	ds_read_b128 v[162:165], v184 offset:36864
	ds_read_b128 v[166:169], v184 offset:37888
	ds_read_b128 v[178:181], v184 offset:38912
	ds_read_b128 v[186:189], v184 offset:39936
	global_load_lds_dwordx4 v[190:191], off
	v_lshl_add_u64 v[190:191], s[2:3], 0, v[172:173]
	s_mov_b32 m0, s77
	s_nop 0
	global_load_lds_dwordx4 v[190:191], off
	s_waitcnt lgkmcnt(8)
	s_add_i32 s2, 0, 0x1c000
	s_add_i32 s3, s12, s54
	v_add_u32_e32 v185, s2, v183
	ds_read_b128 v[190:193], v185
	ds_read_b128 v[194:197], v185 offset:1024
	ds_read_b128 v[198:201], v185 offset:2048
	ds_read_b128 v[226:229], v185 offset:3072
	s_barrier
	s_waitcnt lgkmcnt(0)
	s_waitcnt lgkmcnt(0)
	v_mfma_f32_16x16x32_bf16 v[126:129], v[130:133], v[146:149], v[126:129]
	v_mfma_f32_16x16x32_bf16 v[122:125], v[138:141], v[146:149], v[122:125]
	v_mfma_f32_16x16x32_bf16 v[118:121], v[130:133], v[154:157], v[118:121]
	v_mfma_f32_16x16x32_bf16 v[114:117], v[138:141], v[154:157], v[114:117]
	v_mfma_f32_16x16x32_bf16 v[110:113], v[130:133], v[162:165], v[110:113]
	v_mfma_f32_16x16x32_bf16 v[106:109], v[138:141], v[162:165], v[106:109]
	v_mfma_f32_16x16x32_bf16 v[102:105], v[130:133], v[178:181], v[102:105]
	v_mfma_f32_16x16x32_bf16 v[98:101], v[138:141], v[178:181], v[98:101]
	v_mfma_f32_16x16x32_bf16 v[126:129], v[134:137], v[150:153], v[126:129]
	v_mfma_f32_16x16x32_bf16 v[122:125], v[142:145], v[150:153], v[122:125]
	v_mfma_f32_16x16x32_bf16 v[118:121], v[134:137], v[158:161], v[118:121]
	v_mfma_f32_16x16x32_bf16 v[114:117], v[142:145], v[158:161], v[114:117]
	v_mfma_f32_16x16x32_bf16 v[110:113], v[134:137], v[166:169], v[110:113]
	v_mfma_f32_16x16x32_bf16 v[106:109], v[142:145], v[166:169], v[106:109]
	v_mfma_f32_16x16x32_bf16 v[102:105], v[134:137], v[186:189], v[102:105]
	v_mfma_f32_16x16x32_bf16 v[98:101], v[142:145], v[186:189], v[98:101]
	s_waitcnt lgkmcnt(0)
	s_waitcnt lgkmcnt(0)
	v_mfma_f32_16x16x32_bf16 v[62:65], v[190:193], v[146:149], v[62:65]
	v_mfma_f32_16x16x32_bf16 v[58:61], v[198:201], v[146:149], v[58:61]
	v_mfma_f32_16x16x32_bf16 v[54:57], v[190:193], v[154:157], v[54:57]
	v_mfma_f32_16x16x32_bf16 v[50:53], v[198:201], v[154:157], v[50:53]
	v_mfma_f32_16x16x32_bf16 v[46:49], v[190:193], v[162:165], v[46:49]
	v_mfma_f32_16x16x32_bf16 v[42:45], v[198:201], v[162:165], v[42:45]
	v_mfma_f32_16x16x32_bf16 v[38:41], v[190:193], v[178:181], v[38:41]
	v_mfma_f32_16x16x32_bf16 v[34:37], v[198:201], v[178:181], v[34:37]
	v_mfma_f32_16x16x32_bf16 v[62:65], v[194:197], v[150:153], v[62:65]
	v_mfma_f32_16x16x32_bf16 v[58:61], v[226:229], v[150:153], v[58:61]
	v_mfma_f32_16x16x32_bf16 v[54:57], v[194:197], v[158:161], v[54:57]
	v_mfma_f32_16x16x32_bf16 v[50:53], v[226:229], v[158:161], v[50:53]
	v_mfma_f32_16x16x32_bf16 v[46:49], v[194:197], v[166:169], v[46:49]
	v_mfma_f32_16x16x32_bf16 v[42:45], v[226:229], v[166:169], v[42:45]
	v_mfma_f32_16x16x32_bf16 v[38:41], v[194:197], v[186:189], v[38:41]
	v_mfma_f32_16x16x32_bf16 v[34:37], v[226:229], v[186:189], v[34:37]
	s_mov_b32 m0, s80
	v_lshl_add_u64 v[234:235], v[234:235], 0, s[20:21]
	s_barrier
	ds_read_b128 v[146:149], v184 offset:49152
	ds_read_b128 v[150:153], v184 offset:50176
	ds_read_b128 v[154:157], v184 offset:51200
	ds_read_b128 v[158:161], v184 offset:52224
	ds_read_b128 v[162:165], v184 offset:53248
	ds_read_b128 v[166:169], v184 offset:54272
	ds_read_b128 v[178:181], v184 offset:55296
	ds_read_b128 v[186:189], v184 offset:56320
	global_load_lds_dwordx4 v[234:235], off
	v_lshl_add_u64 v[236:237], v[236:237], 0, s[20:21]
	s_mov_b32 m0, s81
	s_nop 0
	global_load_lds_dwordx4 v[236:237], off
	v_lshl_add_u64 v[230:231], v[230:231], 0, s[20:21]
	s_mov_b32 m0, s3
	s_nop 0
	global_load_lds_dwordx4 v[230:231], off
	v_lshl_add_u64 v[230:231], v[232:233], 0, s[20:21]
	s_add_i32 m0, s3, 0x2000
	s_nop 0
	global_load_lds_dwordx4 v[230:231], off
	s_add_i32 s2, s2, s54
	v_lshl_add_u64 v[242:243], v[242:243], 0, s[20:21]
	s_mov_b32 m0, s2
	s_nop 0
	global_load_lds_dwordx4 v[242:243], off
	v_lshl_add_u64 v[244:245], v[244:245], 0, s[20:21]
	s_add_i32 m0, s2, 0x2000
	s_nop 0
	global_load_lds_dwordx4 v[244:245], off
	s_waitcnt vmcnt(6)
	s_barrier
	s_waitcnt lgkmcnt(0)
	s_waitcnt lgkmcnt(0)
	v_mfma_f32_16x16x32_bf16 v[94:97], v[130:133], v[146:149], v[94:97]
	v_mfma_f32_16x16x32_bf16 v[90:93], v[138:141], v[146:149], v[90:93]
	v_mfma_f32_16x16x32_bf16 v[86:89], v[130:133], v[154:157], v[86:89]
	v_mfma_f32_16x16x32_bf16 v[82:85], v[138:141], v[154:157], v[82:85]
	v_mfma_f32_16x16x32_bf16 v[78:81], v[130:133], v[162:165], v[78:81]
	v_mfma_f32_16x16x32_bf16 v[74:77], v[138:141], v[162:165], v[74:77]
	v_mfma_f32_16x16x32_bf16 v[70:73], v[130:133], v[178:181], v[70:73]
	v_mfma_f32_16x16x32_bf16 v[66:69], v[138:141], v[178:181], v[66:69]
	v_mfma_f32_16x16x32_bf16 v[94:97], v[134:137], v[150:153], v[94:97]
	v_mfma_f32_16x16x32_bf16 v[90:93], v[142:145], v[150:153], v[90:93]
	v_mfma_f32_16x16x32_bf16 v[86:89], v[134:137], v[158:161], v[86:89]
	v_mfma_f32_16x16x32_bf16 v[82:85], v[142:145], v[158:161], v[82:85]
	v_mfma_f32_16x16x32_bf16 v[78:81], v[134:137], v[166:169], v[78:81]
	v_mfma_f32_16x16x32_bf16 v[74:77], v[142:145], v[166:169], v[74:77]
	v_mfma_f32_16x16x32_bf16 v[70:73], v[134:137], v[186:189], v[70:73]
	v_mfma_f32_16x16x32_bf16 v[66:69], v[142:145], v[186:189], v[66:69]
	v_mfma_f32_16x16x32_bf16 v[30:33], v[190:193], v[146:149], v[30:33]
	v_mfma_f32_16x16x32_bf16 v[26:29], v[198:201], v[146:149], v[26:29]
	v_mfma_f32_16x16x32_bf16 v[22:25], v[190:193], v[154:157], v[22:25]
	v_mfma_f32_16x16x32_bf16 v[18:21], v[198:201], v[154:157], v[18:21]
	v_mfma_f32_16x16x32_bf16 v[14:17], v[190:193], v[162:165], v[14:17]
	v_mfma_f32_16x16x32_bf16 v[10:13], v[198:201], v[162:165], v[10:13]
	v_mfma_f32_16x16x32_bf16 v[6:9], v[190:193], v[178:181], v[6:9]
	v_mfma_f32_16x16x32_bf16 v[2:5], v[198:201], v[178:181], v[2:5]
	v_mfma_f32_16x16x32_bf16 v[30:33], v[194:197], v[150:153], v[30:33]
	v_mfma_f32_16x16x32_bf16 v[26:29], v[226:229], v[150:153], v[26:29]
	v_mfma_f32_16x16x32_bf16 v[22:25], v[194:197], v[158:161], v[22:25]
	v_mfma_f32_16x16x32_bf16 v[18:21], v[226:229], v[158:161], v[18:21]
	v_mfma_f32_16x16x32_bf16 v[14:17], v[194:197], v[166:169], v[14:17]
	v_mfma_f32_16x16x32_bf16 v[10:13], v[226:229], v[166:169], v[10:13]
	v_mfma_f32_16x16x32_bf16 v[6:9], v[194:197], v[186:189], v[6:9]
	v_mfma_f32_16x16x32_bf16 v[2:5], v[226:229], v[186:189], v[2:5]
	s_add_u32 s34, s34, 0x100
	s_addc_u32 s35, s35, 0
	s_add_u32 s89, s89, 0x100
	s_addc_u32 s90, s90, 0
	s_cmp_ge_i32 s91, s44
	s_mov_b32 s2, s91
	s_barrier
	s_cbranch_scc0 .LBB0_182
	s_cmp_lt_i32 s86, 64
	s_cselect_b64 s[34:35], -1, 0
	s_ashr_i32 s2, s45, 8
	s_ashr_i32 s3, s2, 31
	s_lshl_b64 s[2:3], s[2:3], 18
	s_add_u32 s2, s2, 0x3232000
	s_addc_u32 s3, s3, 0
	s_cmp_gt_i32 s86, 63
	s_cselect_b32 s12, 0x6000, 0
	s_cselect_b32 s45, s3, 0
	s_cselect_b32 s44, s2, 0
	s_add_u32 s12, s78, s12
	s_addc_u32 s13, s79, 0
	s_lshl_b32 s2, s87, 8
	s_ashr_i32 s3, s2, 31
	s_lshl_b64 s[2:3], s[2:3], 2
	s_add_u32 s12, s12, s2
	s_addc_u32 s13, s13, s3
	v_readlane_b32 s88, v254, 38
	s_add_u32 s42, s12, s88
	s_addc_u32 s43, s13, 0
	global_load_dwordx4 v[134:137], v0, s[42:43]
	global_load_dwordx4 v[130:133], v0, s[42:43] offset:64
	v_lshl_add_u32 v138, s86, 8, v182
	v_ashrrev_i32_e32 v139, 31, v138
	v_readlane_b32 s12, v252, 5
	v_lshlrev_b64 v[138:139], 12, v[138:139]
	v_readlane_b32 s13, v252, 6
	v_readlane_b32 s89, v254, 39
	s_and_b64 vcc, exec, s[34:35]
	v_lshl_add_u64 v[138:139], s[12:13], 0, v[138:139]
	v_lshl_add_u64 v[138:139], v[138:139], 0, s[2:3]
	v_lshl_add_u64 v[138:139], v[138:139], 0, s[88:89]
	v_lshl_add_u64 v[178:179], v[138:139], 0, v[0:1]
	v_lshl_add_u64 v[180:181], v[178:179], 0, s[22:23]
	v_readfirstlane_b32 s88, v178
	v_readfirstlane_b32 s89, v179
	v_and_b32_e32 v178, 15, v202
	v_bfe_u32 v179, v202, 4, 2
	v_lshlrev_b32_e32 v178, 12, v178
	v_lshl_or_b32 v178, v179, 4, v178
	s_mov_b32 s13, 0
	s_and_b64 vcc, exec, s[34:35]
	s_cbranch_vccz .Lre_nf
	v_readlane_b32 s2, v252, 2
	v_readlane_b32 s3, v255, 14
	v_readlane_b32 s12, v255, 12
	s_cmp_eq_u32 s2, 0x100
	s_cbranch_scc0 .Lre_nf
	s_cmp_eq_u32 s3, 5
	s_cbranch_scc1 .Lre_f
	s_cmp_eq_u32 s3, 8
	s_cbranch_scc0 .Lre_nf
